# attn task loop: static s_setprio 1 for waves 4-7
# baseline (speedup 1.0000x reference)
.LBB0_214:
	s_and_b64 vcc, exec, s[4:5]
	s_cbranch_vccz .LBB0_359
	v_readlane_b32 s4, v254, 5
	s_mov_b32 s0, s4
	v_readlane_b32 s5, v254, 6
	v_writelane_b32 v254, s0, 5
	s_ashr_i32 s5, s4, 31
	s_lshl_b64 s[4:5], s[4:5], 2
	v_writelane_b32 v254, s1, 6
	s_nop 0
	v_readlane_b32 s10, v254, 7
	v_readlane_b32 s11, v254, 8
	s_load_dwordx2 s[8:9], s[10:11], 0x108
	s_waitcnt lgkmcnt(0)
	s_add_u32 s4, s8, s4
	s_addc_u32 s5, s9, s5
	v_writelane_b32 v254, s4, 14
	s_add_u32 s6, s8, 0x35a5000
	s_addc_u32 s7, s9, 0
	v_writelane_b32 v254, s5, 15
	v_writelane_b32 v254, s6, 16
	s_load_dwordx2 s[4:5], s[10:11], 0x98
	s_nop 0
	v_writelane_b32 v254, s7, 17
	s_add_u32 s6, s8, 0x11925000
	s_addc_u32 s7, s9, 0
	v_writelane_b32 v254, s6, 18
	s_nop 1
	v_writelane_b32 v254, s7, 19
	s_add_u32 s6, s8, 0x1525000
	s_addc_u32 s7, s9, 0
	v_writelane_b32 v254, s6, 20
	s_nop 1
	v_writelane_b32 v254, s7, 21
	s_nop 0
	v_readlane_b32 s6, v254, 11
	v_readlane_b32 s7, v254, 12
	s_mov_b32 s0, s6
	s_lshl_b32 s6, s6, 6
	s_ashr_i32 s7, s6, 31
	s_lshl_b64 s[6:7], s[6:7], 2
	s_waitcnt lgkmcnt(0)
	s_add_u32 s4, s4, s6
	s_addc_u32 s5, s5, s7
	v_writelane_b32 v254, s4, 22
	s_nop 1
	v_writelane_b32 v254, s5, 23
	s_add_u32 s4, s8, 0x1ac85000
	s_addc_u32 s5, s9, 0
	v_writelane_b32 v254, s4, 24
	s_nop 1
	v_writelane_b32 v254, s5, 25
	s_add_u32 s4, s8, 0x19385000
	s_addc_u32 s5, s9, 0
	v_writelane_b32 v254, s4, 26
	s_nop 1
	v_writelane_b32 v254, s5, 27
	s_add_u32 s4, s8, 0x1b4c5000
	s_addc_u32 s5, s9, 0
	v_writelane_b32 v254, s4, 28
	s_nop 1
	v_writelane_b32 v254, s5, 29
	s_add_u32 s4, s8, 0x19b85000
	s_addc_u32 s5, s9, 0
	v_writelane_b32 v254, s4, 30
	s_nop 1
	v_writelane_b32 v254, s5, 31
	s_add_u32 s4, s8, 0x1b0a5000
	s_addc_u32 s5, s9, 0
	v_writelane_b32 v254, s4, 32
	s_nop 1
	v_writelane_b32 v254, s5, 33
	s_add_u32 s4, s8, 0x19785000
	s_addc_u32 s5, s9, 0
	v_writelane_b32 v254, s4, 34
	s_nop 1
	v_writelane_b32 v254, s5, 35
	s_add_u32 s4, s8, 0x19285000
	s_addc_u32 s5, s9, 0
	v_writelane_b32 v254, s4, 36
	s_nop 1
	v_writelane_b32 v254, s5, 37
	s_add_u32 s4, s8, 0x1b5cd000
	s_addc_u32 s5, s9, 0
	v_writelane_b32 v254, s4, 38
	s_nop 1
	v_writelane_b32 v254, s5, 39
	s_add_u32 s4, s8, 0x1c64d000
	s_addc_u32 s5, s9, 0
	v_writelane_b32 v254, s4, 40
	s_nop 1
	v_writelane_b32 v254, s5, 41
	s_add_u32 s4, s8, 0x19c85000
	s_addc_u32 s5, s9, 0
	v_writelane_b32 v254, s4, 42
	s_nop 1
	v_writelane_b32 v254, s5, 43
	s_lshl_b32 s4, s0, 1
	s_ashr_i32 s5, s4, 31
	s_lshl_b64 s[4:5], s[4:5], 2
	s_add_u32 s4, s8, s4
	s_addc_u32 s5, s9, s5
	v_writelane_b32 v254, s4, 44
	s_nop 1
	v_writelane_b32 v254, s5, 45
	v_readlane_b32 s6, v253, 43
	s_nop 1
	s_cmpk_lt_u32 s6, 0x100
	s_cbranch_scc1 .Lattn_prio_skip
	s_setprio 1
.Lattn_prio_skip:
	s_mov_b64 s[4:5], 0
	s_branch .LBB0_219

.LBB0_358:
	s_setprio 0
	s_or_b64 exec, exec, s[4:5]
	s_barrier
